# attention unit-order reversal table 0x44 instead of 0x04 (one more group runs its short unit first)
# baseline (speedup 1.0000x reference)
.Lst_norm:
	s_ashr_i32 s6, s2, 31
	s_lshr_b32 s6, s6, 29
	s_add_i32 s6, s2, s6
	s_and_b32 s7, s6, -8
	s_ashr_i32 s5, s3, 3
	s_sub_i32 s66, s2, s7
	s_mul_i32 s5, s5, s66
	s_ashr_i32 s67, s6, 3
	s_and_b32 s4, s3, 7
	s_add_i32 s5, s5, s67
	s_cmpk_eq_i32 s3, 0x100
	s_cselect_b64 s[8:9], -1, 0
	s_cmpk_lg_i32 s3, 0x100
	s_mov_b64 s[14:15], s[24:25]
	s_cselect_b64 s[12:13], -1, 0
	s_add_u32 s68, s14, 0x5000000
	s_addc_u32 s69, s15, 0
	s_add_u32 s73, s14, 0x6000000
	s_addc_u32 s74, s15, 0
	s_add_u32 s75, s14, 0x7000000
	s_addc_u32 s76, s15, 0
	s_cmp_eq_u32 s4, 0
	s_cselect_b32 s77, s5, s2
	s_and_b32 s5, s77, 3
	s_and_b32 s6, s77, 2
	s_add_i32 s6, s6, s5
	s_and_b32 s4, s77, 4
	s_ashr_i32 s78, s77, 3
	s_sub_i32 s7, 13, s6
	s_xor_b32 s10, s5, 15
	s_sub_i32 s16, 13, s5
	s_add_i32 s17, s5, 2
	s_or_b32 s18, s5, 4
	s_cmp_lt_u32 s5, 2
	s_cselect_b32 s5, s10, s16
	s_cselect_b32 s10, s17, s18
	s_cmp_eq_u32 s4, 0
	s_cselect_b32 s79, s5, s7
	s_cselect_b32 s80, s10, s6
	s_lshr_b32 s98, s2, 3
	s_and_b32 s98, s98, 7
	s_lshr_b32 s98, 0x44, s98
	s_bitcmp1_b32 s98, 0
	s_cbranch_scc0 .Lnorev
	s_mov_b32 s98, s79
	s_mov_b32 s79, s80
	s_mov_b32 s80, s98
